# lazy-rescale branch test shortened (v_cmp_nge + s_cbranch_vccnz instead of v_cmp_ge + s_cmp_eq_u64 + scc branch) on top of early tile barrier and XOR-derived K bases
# baseline (speedup 1.0000x reference)
.LBB0_187:
	s_nop 9
	v_max_f32_e32 v188, v19, v19
	v_max_f32_e32 v189, v18, v18
	v_max_f32_e32 v188, v189, v188
	v_max3_f32 v188, v188, v20, v21
	v_max3_f32 v188, v188, v22, v23
	v_max3_f32 v188, v188, v24, v25
	v_max3_f32 v188, v188, v26, v27
	v_max3_f32 v188, v188, v28, v29
	v_max3_f32 v188, v188, v30, v31
	v_max3_f32 v188, v188, v32, v33
	v_max3_f32 v188, v188, v2, v3
	v_max3_f32 v188, v188, v4, v5
	v_max3_f32 v188, v188, v6, v7
	v_max3_f32 v188, v188, v8, v9
	v_max3_f32 v188, v188, v10, v11
	v_max3_f32 v188, v188, v12, v13
	v_max3_f32 v188, v188, v14, v15
	v_max3_f32 v188, v188, v16, v17
	v_mov_b32_e32 v189, v188
	s_nop 1
	v_permlane32_swap_b32_e32 v188, v189
	v_max_f32_e32 v189, v189, v189
	v_max_f32_e32 v188, v188, v188
	v_max_f32_e32 v189, v188, v189
	v_sub_f32_e32 v188, v189, v186
	v_mul_f32_e32 v188, 0x3db504f3, v188
	v_cmp_nge_f32_e32 vcc, s50, v188
	v_mov_b32_e32 v188, 1.0
	s_cbranch_vccnz .LBB0_200

.LBB0_196:
	s_nop 9
	v_max_f32_e32 v193, v19, v19
	v_max_f32_e32 v195, v18, v18
	v_max_f32_e32 v193, v195, v193
	v_max3_f32 v193, v193, v20, v21
	v_max3_f32 v193, v193, v22, v23
	v_max3_f32 v193, v193, v24, v25
	v_max3_f32 v193, v193, v26, v27
	v_max3_f32 v193, v193, v28, v29
	v_max3_f32 v193, v193, v30, v31
	v_max3_f32 v193, v193, v32, v33
	v_max3_f32 v193, v193, v2, v3
	v_max3_f32 v193, v193, v4, v5
	v_max3_f32 v193, v193, v6, v7
	v_max3_f32 v193, v193, v8, v9
	v_max3_f32 v193, v193, v10, v11
	v_max3_f32 v193, v193, v12, v13
	v_max3_f32 v193, v193, v14, v15
	v_max3_f32 v193, v193, v16, v17
	v_mov_b32_e32 v195, v193
	s_nop 1
	v_permlane32_swap_b32_e32 v193, v195
	v_max_f32_e32 v195, v195, v195
	v_max_f32_e32 v193, v193, v193
	v_max_f32_e32 v195, v193, v195
	v_sub_f32_e32 v193, v195, v186
	v_mul_f32_e32 v193, 0x3db504f3, v193
	v_cmp_nge_f32_e32 vcc, s50, v193
	v_mov_b32_e32 v193, 1.0
	s_cbranch_vccnz .LBB0_201
